# EpiQKV rope: lane^16 exchange via ds_bpermute (1 op) instead of mov+mov+permlane16_swap+cndmask
# speedup vs baseline: 1.0039x; 1.0039x over previous
.LBB0_186:
	v_xor_b32_e32 v250, 16, v199
	v_lshlrev_b32_e32 v250, 2, v250
	s_cmp_lt_i32 s34, 8
	s_cselect_b64 s[12:13], -1, 0
	s_lshl_b32 s25, s10, 8
	v_add_u32_e32 v184, s25, v155
	v_ashrrev_i32_e32 v185, 31, v184
	v_lshl_add_u64 v[42:43], v[184:185], 3, s[68:69]
	global_load_dwordx2 v[186:187], v[42:43], off
	s_and_b64 s[12:13], s[22:23], s[12:13]
	v_cndmask_b32_e64 v0, 0, 1, s[12:13]
	v_cmp_ne_u32_e64 s[10:11], 1, v0
	s_andn2_b64 vcc, exec, s[12:13]
	s_cbranch_vccnz .LBB0_188
	v_lshlrev_b32_e32 v0, 6, v184
	v_and_b32_e32 v0, 0x3f3c0, v0
	global_load_dwordx4 v[58:61], v0, s[38:39] offset:32
	global_load_dwordx4 v[70:73], v0, s[38:39] offset:48
	global_load_dwordx4 v[42:45], v0, s[38:39] offset:16
	global_load_dwordx4 v[54:57], v0, s[38:39]
	s_waitcnt vmcnt(0)
	v_xor_b32_e32 v0, 0x80000000, v58
	v_xor_b32_e32 v185, 0x80000000, v59
	v_xor_b32_e32 v193, 0x80000000, v60
	v_xor_b32_e32 v200, 0x80000000, v61
	v_xor_b32_e32 v201, 0x80000000, v70
	v_xor_b32_e32 v202, 0x80000000, v71
	v_xor_b32_e32 v203, 0x80000000, v72
	v_xor_b32_e32 v204, 0x80000000, v73
	v_cndmask_b32_e64 v61, v61, v200, s[6:7]
	v_cndmask_b32_e64 v60, v60, v193, s[6:7]
	v_cndmask_b32_e64 v59, v59, v185, s[6:7]
	v_cndmask_b32_e64 v58, v58, v0, s[6:7]
	v_cndmask_b32_e64 v73, v73, v204, s[6:7]
	v_cndmask_b32_e64 v72, v72, v203, s[6:7]
	v_cndmask_b32_e64 v71, v71, v202, s[6:7]
	v_cndmask_b32_e64 v70, v70, v201, s[6:7]
.LBB0_188:
	s_waitcnt vmcnt(0)
	v_ffbh_u32_e32 v0, v187
	v_min_u32_e32 v0, 32, v0
	v_lshlrev_b64 v[186:187], v0, v[186:187]
	v_min_u32_e32 v185, 1, v186
	v_or_b32_e32 v185, v187, v185
	v_cvt_f32_u32_e32 v185, v185
	v_sub_u32_e32 v0, 32, v0
	s_cmp_lt_u32 s34, 4
	s_cselect_b64 vcc, -1, 0
	v_ldexp_f32 v0, v185, v0
	v_mul_f32_e32 v0, 0x37800000, v0
	v_fmamk_f32 v0, v0, 0x3a800000, v195
	v_rsq_f32_e32 v0, v0
	v_cndmask_b32_e32 v185, 1.0, v197, vcc
	s_and_b64 vcc, exec, s[10:11]
	v_mul_f32_e32 v186, v185, v0
	v_pk_mul_f32 v[144:145], v[144:145], v[186:187] op_sel_hi:[1,0]
	v_pk_mul_f32 v[142:143], v[142:143], v[186:187] op_sel_hi:[1,0]
	v_pk_mul_f32 v[140:141], v[140:141], v[186:187] op_sel_hi:[1,0]
	v_pk_mul_f32 v[138:139], v[138:139], v[186:187] op_sel_hi:[1,0]
	s_cbranch_vccnz .LBB0_190
	ds_bpermute_b32 v200, v250, v142
	ds_bpermute_b32 v201, v250, v143
	ds_bpermute_b32 v202, v250, v144
	ds_bpermute_b32 v203, v250, v145
	ds_bpermute_b32 v204, v250, v138
	ds_bpermute_b32 v205, v250, v139
	ds_bpermute_b32 v206, v250, v140
	ds_bpermute_b32 v207, v250, v141
	s_waitcnt lgkmcnt(0)
	v_pk_mul_f32 v[202:203], v[60:61], v[202:203]
	v_pk_mul_f32 v[200:201], v[58:59], v[200:201]
	v_pk_mul_f32 v[206:207], v[72:73], v[206:207]
	v_pk_mul_f32 v[204:205], v[70:71], v[204:205]
	v_pk_fma_f32 v[200:201], v[142:143], v[54:55], v[200:201]
	v_pk_fma_f32 v[202:203], v[144:145], v[56:57], v[202:203]
	v_pk_fma_f32 v[204:205], v[138:139], v[42:43], v[204:205]
	v_pk_fma_f32 v[206:207], v[140:141], v[44:45], v[206:207]
	v_cndmask_b32_e64 v145, v145, v203, s[4:5]
	v_cndmask_b32_e64 v144, v144, v202, s[4:5]
	v_cndmask_b32_e64 v143, v143, v201, s[4:5]
	v_cndmask_b32_e64 v142, v142, v200, s[4:5]
	v_cndmask_b32_e64 v141, v141, v207, s[4:5]
	v_cndmask_b32_e64 v140, v140, v206, s[4:5]
	v_cndmask_b32_e64 v139, v139, v205, s[4:5]
	v_cndmask_b32_e64 v138, v138, v204, s[4:5]
.LBB0_190:
	v_cvt_pk_bf16_f32 v142, v142, v143
	v_cvt_pk_bf16_f32 v143, v144, v145
	v_cvt_pk_bf16_f32 v144, v138, v139
	v_mov_b64_e32 v[138:139], s[56:57]
	s_lshl_b32 s34, s34, 8
	v_mad_i64_i32 v[138:139], s[12:13], v184, s87, v[138:139]
	s_ashr_i32 s35, s34, 31
	v_lshl_add_u64 v[138:139], s[34:35], 1, v[138:139]
	s_lshl_b32 s90, s14, 1
	v_mov_b32_e32 v187, v186
	v_cvt_pk_bf16_f32 v145, v140, v141
	v_lshl_add_u64 v[138:139], v[138:139], 0, s[90:91]
	v_lshlrev_b32_e32 v0, 1, v154
	v_mov_b32_e32 v140, v186
	v_mov_b32_e32 v141, v186
	v_lshl_add_u64 v[138:139], v[138:139], 0, v[0:1]
	v_pk_mul_f32 v[136:137], v[136:137], v[140:141]
	v_pk_mul_f32 v[134:135], v[134:135], v[186:187]
	v_pk_mul_f32 v[132:133], v[132:133], v[140:141]
	s_and_b64 vcc, exec, s[10:11]
	v_pk_mul_f32 v[130:131], v[130:131], v[186:187]
	global_store_dwordx4 v[138:139], v[142:145], off
	s_cbranch_vccnz .LBB0_192
	ds_bpermute_b32 v140, v250, v134
	ds_bpermute_b32 v141, v250, v135
	ds_bpermute_b32 v142, v250, v136
	ds_bpermute_b32 v143, v250, v137
	ds_bpermute_b32 v144, v250, v130
	ds_bpermute_b32 v145, v250, v131
	ds_bpermute_b32 v186, v250, v132
	ds_bpermute_b32 v187, v250, v133
	s_waitcnt lgkmcnt(0)
	v_pk_mul_f32 v[142:143], v[60:61], v[142:143]
	v_pk_mul_f32 v[140:141], v[58:59], v[140:141]
	v_pk_mul_f32 v[186:187], v[72:73], v[186:187]
	v_pk_mul_f32 v[144:145], v[70:71], v[144:145]
	v_pk_fma_f32 v[140:141], v[134:135], v[54:55], v[140:141]
	v_pk_fma_f32 v[142:143], v[136:137], v[56:57], v[142:143]
	v_pk_fma_f32 v[144:145], v[130:131], v[42:43], v[144:145]
	v_pk_fma_f32 v[186:187], v[132:133], v[44:45], v[186:187]
	v_cndmask_b32_e64 v137, v137, v143, s[4:5]
	v_cndmask_b32_e64 v136, v136, v142, s[4:5]
	v_cndmask_b32_e64 v135, v135, v141, s[4:5]
	v_cndmask_b32_e64 v134, v134, v140, s[4:5]
	v_cndmask_b32_e64 v133, v133, v187, s[4:5]
	v_cndmask_b32_e64 v132, v132, v186, s[4:5]
	v_cndmask_b32_e64 v131, v131, v145, s[4:5]
	v_cndmask_b32_e64 v130, v130, v144, s[4:5]

.LBB0_194:
	s_waitcnt vmcnt(0)
	v_ffbh_u32_e32 v131, v133
	v_min_u32_e32 v131, 32, v131
	v_lshlrev_b64 v[132:133], v131, v[132:133]
	v_min_u32_e32 v132, 1, v132
	v_or_b32_e32 v132, v133, v132
	v_cvt_f32_u32_e32 v132, v132
	v_sub_u32_e32 v131, 32, v131
	s_and_b64 vcc, exec, s[10:11]
	v_ldexp_f32 v131, v132, v131
	v_mul_f32_e32 v131, 0x37800000, v131
	v_fmamk_f32 v131, v131, 0x3a800000, v195
	v_rsq_f32_e32 v131, v131
	s_nop 0
	v_mul_f32_e32 v132, v185, v131
	v_pk_mul_f32 v[128:129], v[128:129], v[132:133] op_sel_hi:[1,0]
	v_pk_mul_f32 v[126:127], v[126:127], v[132:133] op_sel_hi:[1,0]
	v_pk_mul_f32 v[124:125], v[124:125], v[132:133] op_sel_hi:[1,0]
	v_pk_mul_f32 v[122:123], v[122:123], v[132:133] op_sel_hi:[1,0]
	s_cbranch_vccnz .LBB0_196
	ds_bpermute_b32 v134, v250, v126
	ds_bpermute_b32 v135, v250, v127
	ds_bpermute_b32 v136, v250, v128
	ds_bpermute_b32 v137, v250, v129
	ds_bpermute_b32 v138, v250, v122
	ds_bpermute_b32 v139, v250, v123
	ds_bpermute_b32 v140, v250, v124
	ds_bpermute_b32 v141, v250, v125
	s_waitcnt lgkmcnt(0)
	v_pk_mul_f32 v[136:137], v[60:61], v[136:137]
	v_pk_mul_f32 v[134:135], v[58:59], v[134:135]
	v_pk_mul_f32 v[140:141], v[72:73], v[140:141]
	v_pk_mul_f32 v[138:139], v[70:71], v[138:139]
	v_pk_fma_f32 v[134:135], v[126:127], v[54:55], v[134:135]
	v_pk_fma_f32 v[136:137], v[128:129], v[56:57], v[136:137]
	v_pk_fma_f32 v[138:139], v[122:123], v[42:43], v[138:139]
	v_pk_fma_f32 v[140:141], v[124:125], v[44:45], v[140:141]
	v_cndmask_b32_e64 v129, v129, v137, s[4:5]
	v_cndmask_b32_e64 v128, v128, v136, s[4:5]
	v_cndmask_b32_e64 v127, v127, v135, s[4:5]
	v_cndmask_b32_e64 v126, v126, v134, s[4:5]
	v_cndmask_b32_e64 v125, v125, v141, s[4:5]
	v_cndmask_b32_e64 v124, v124, v140, s[4:5]
	v_cndmask_b32_e64 v123, v123, v139, s[4:5]
	v_cndmask_b32_e64 v122, v122, v138, s[4:5]
.LBB0_196:
	v_cvt_pk_bf16_f32 v126, v126, v127
	v_cvt_pk_bf16_f32 v127, v128, v129
	v_cvt_pk_bf16_f32 v128, v122, v123
	v_mov_b64_e32 v[122:123], s[56:57]
	v_mad_i64_i32 v[122:123], s[12:13], v130, s87, v[122:123]
	v_lshl_add_u64 v[122:123], s[34:35], 1, v[122:123]
	v_mov_b32_e32 v133, v132
	v_cvt_pk_bf16_f32 v129, v124, v125
	v_lshl_add_u64 v[122:123], v[122:123], 0, s[90:91]
	v_mov_b32_e32 v124, v132
	v_mov_b32_e32 v125, v132
	v_lshl_add_u64 v[122:123], v[122:123], 0, v[0:1]
	v_pk_mul_f32 v[120:121], v[120:121], v[124:125]
	v_pk_mul_f32 v[118:119], v[118:119], v[132:133]
	v_pk_mul_f32 v[116:117], v[116:117], v[124:125]
	s_and_b64 vcc, exec, s[10:11]
	v_pk_mul_f32 v[114:115], v[114:115], v[132:133]
	global_store_dwordx4 v[122:123], v[126:129], off
	s_cbranch_vccnz .LBB0_198
	ds_bpermute_b32 v124, v250, v118
	ds_bpermute_b32 v125, v250, v119
	ds_bpermute_b32 v126, v250, v120
	ds_bpermute_b32 v127, v250, v121
	ds_bpermute_b32 v128, v250, v114
	ds_bpermute_b32 v129, v250, v115
	ds_bpermute_b32 v130, v250, v116
	ds_bpermute_b32 v131, v250, v117
	s_waitcnt lgkmcnt(0)
	v_pk_mul_f32 v[126:127], v[60:61], v[126:127]
	v_pk_mul_f32 v[124:125], v[58:59], v[124:125]
	v_pk_mul_f32 v[130:131], v[72:73], v[130:131]
	v_pk_mul_f32 v[128:129], v[70:71], v[128:129]
	v_pk_fma_f32 v[124:125], v[118:119], v[54:55], v[124:125]
	v_pk_fma_f32 v[126:127], v[120:121], v[56:57], v[126:127]
	v_pk_fma_f32 v[128:129], v[114:115], v[42:43], v[128:129]
	v_pk_fma_f32 v[130:131], v[116:117], v[44:45], v[130:131]
	v_cndmask_b32_e64 v121, v121, v127, s[4:5]
	v_cndmask_b32_e64 v120, v120, v126, s[4:5]
	v_cndmask_b32_e64 v119, v119, v125, s[4:5]
	v_cndmask_b32_e64 v118, v118, v124, s[4:5]
	v_cndmask_b32_e64 v117, v117, v131, s[4:5]
	v_cndmask_b32_e64 v116, v116, v130, s[4:5]
	v_cndmask_b32_e64 v115, v115, v129, s[4:5]
	v_cndmask_b32_e64 v114, v114, v128, s[4:5]

.LBB0_200:
	s_waitcnt vmcnt(0)
	v_ffbh_u32_e32 v115, v117
	v_min_u32_e32 v115, 32, v115
	v_lshlrev_b64 v[116:117], v115, v[116:117]
	v_min_u32_e32 v116, 1, v116
	v_or_b32_e32 v116, v117, v116
	v_cvt_f32_u32_e32 v116, v116
	v_sub_u32_e32 v115, 32, v115
	s_and_b64 vcc, exec, s[10:11]
	v_ldexp_f32 v115, v116, v115
	v_mul_f32_e32 v115, 0x37800000, v115
	v_fmamk_f32 v115, v115, 0x3a800000, v195
	v_rsq_f32_e32 v115, v115
	s_nop 0
	v_mul_f32_e32 v116, v185, v115
	v_pk_mul_f32 v[112:113], v[112:113], v[116:117] op_sel_hi:[1,0]
	v_pk_mul_f32 v[110:111], v[110:111], v[116:117] op_sel_hi:[1,0]
	v_pk_mul_f32 v[108:109], v[108:109], v[116:117] op_sel_hi:[1,0]
	v_pk_mul_f32 v[106:107], v[106:107], v[116:117] op_sel_hi:[1,0]
	s_cbranch_vccnz .LBB0_202
	ds_bpermute_b32 v118, v250, v110
	ds_bpermute_b32 v119, v250, v111
	ds_bpermute_b32 v120, v250, v112
	ds_bpermute_b32 v121, v250, v113
	ds_bpermute_b32 v122, v250, v106
	ds_bpermute_b32 v123, v250, v107
	ds_bpermute_b32 v124, v250, v108
	ds_bpermute_b32 v125, v250, v109
	s_waitcnt lgkmcnt(0)
	v_pk_mul_f32 v[120:121], v[60:61], v[120:121]
	v_pk_mul_f32 v[118:119], v[58:59], v[118:119]
	v_pk_mul_f32 v[124:125], v[72:73], v[124:125]
	v_pk_mul_f32 v[122:123], v[70:71], v[122:123]
	v_pk_fma_f32 v[118:119], v[110:111], v[54:55], v[118:119]
	v_pk_fma_f32 v[120:121], v[112:113], v[56:57], v[120:121]
	v_pk_fma_f32 v[122:123], v[106:107], v[42:43], v[122:123]
	v_pk_fma_f32 v[124:125], v[108:109], v[44:45], v[124:125]
	v_cndmask_b32_e64 v113, v113, v121, s[4:5]
	v_cndmask_b32_e64 v112, v112, v120, s[4:5]
	v_cndmask_b32_e64 v111, v111, v119, s[4:5]
	v_cndmask_b32_e64 v110, v110, v118, s[4:5]
	v_cndmask_b32_e64 v109, v109, v125, s[4:5]
	v_cndmask_b32_e64 v108, v108, v124, s[4:5]
	v_cndmask_b32_e64 v107, v107, v123, s[4:5]
	v_cndmask_b32_e64 v106, v106, v122, s[4:5]
.LBB0_202:
	v_cvt_pk_bf16_f32 v110, v110, v111
	v_cvt_pk_bf16_f32 v111, v112, v113
	v_cvt_pk_bf16_f32 v112, v106, v107
	v_mov_b64_e32 v[106:107], s[56:57]
	v_mad_i64_i32 v[106:107], s[12:13], v114, s87, v[106:107]
	v_lshl_add_u64 v[106:107], s[34:35], 1, v[106:107]
	v_mov_b32_e32 v117, v116
	v_cvt_pk_bf16_f32 v113, v108, v109
	v_lshl_add_u64 v[106:107], v[106:107], 0, s[90:91]
	v_mov_b32_e32 v108, v116
	v_mov_b32_e32 v109, v116
	v_lshl_add_u64 v[106:107], v[106:107], 0, v[0:1]
	v_pk_mul_f32 v[104:105], v[104:105], v[108:109]
	v_pk_mul_f32 v[102:103], v[102:103], v[116:117]
	v_pk_mul_f32 v[100:101], v[100:101], v[108:109]
	s_and_b64 vcc, exec, s[10:11]
	v_pk_mul_f32 v[98:99], v[98:99], v[116:117]
	global_store_dwordx4 v[106:107], v[110:113], off
	s_cbranch_vccnz .LBB0_204
	ds_bpermute_b32 v108, v250, v102
	ds_bpermute_b32 v109, v250, v103
	ds_bpermute_b32 v110, v250, v104
	ds_bpermute_b32 v111, v250, v105
	ds_bpermute_b32 v112, v250, v98
	ds_bpermute_b32 v113, v250, v99
	ds_bpermute_b32 v114, v250, v100
	ds_bpermute_b32 v115, v250, v101
	s_waitcnt lgkmcnt(0)
	v_pk_mul_f32 v[110:111], v[60:61], v[110:111]
	v_pk_mul_f32 v[108:109], v[58:59], v[108:109]
	v_pk_mul_f32 v[114:115], v[72:73], v[114:115]
	v_pk_mul_f32 v[112:113], v[70:71], v[112:113]
	v_pk_fma_f32 v[108:109], v[102:103], v[54:55], v[108:109]
	v_pk_fma_f32 v[110:111], v[104:105], v[56:57], v[110:111]
	v_pk_fma_f32 v[112:113], v[98:99], v[42:43], v[112:113]
	v_pk_fma_f32 v[114:115], v[100:101], v[44:45], v[114:115]
	v_cndmask_b32_e64 v105, v105, v111, s[4:5]
	v_cndmask_b32_e64 v104, v104, v110, s[4:5]
	v_cndmask_b32_e64 v103, v103, v109, s[4:5]
	v_cndmask_b32_e64 v102, v102, v108, s[4:5]
	v_cndmask_b32_e64 v101, v101, v115, s[4:5]
	v_cndmask_b32_e64 v100, v100, v114, s[4:5]
	v_cndmask_b32_e64 v99, v99, v113, s[4:5]
	v_cndmask_b32_e64 v98, v98, v112, s[4:5]

.LBB0_206:
	s_waitcnt vmcnt(0)
	v_ffbh_u32_e32 v99, v101
	v_min_u32_e32 v99, 32, v99
	v_lshlrev_b64 v[100:101], v99, v[100:101]
	v_min_u32_e32 v100, 1, v100
	v_or_b32_e32 v100, v101, v100
	v_cvt_f32_u32_e32 v100, v100
	v_sub_u32_e32 v99, 32, v99
	s_and_b64 vcc, exec, s[10:11]
	v_ldexp_f32 v99, v100, v99
	v_mul_f32_e32 v99, 0x37800000, v99
	v_fmamk_f32 v99, v99, 0x3a800000, v195
	v_rsq_f32_e32 v99, v99
	s_nop 0
	v_mul_f32_e32 v100, v185, v99
	v_pk_mul_f32 v[96:97], v[96:97], v[100:101] op_sel_hi:[1,0]
	v_pk_mul_f32 v[94:95], v[94:95], v[100:101] op_sel_hi:[1,0]
	v_pk_mul_f32 v[92:93], v[92:93], v[100:101] op_sel_hi:[1,0]
	v_pk_mul_f32 v[90:91], v[90:91], v[100:101] op_sel_hi:[1,0]
	s_cbranch_vccnz .LBB0_208
	ds_bpermute_b32 v102, v250, v94
	ds_bpermute_b32 v103, v250, v95
	ds_bpermute_b32 v104, v250, v96
	ds_bpermute_b32 v105, v250, v97
	ds_bpermute_b32 v106, v250, v90
	ds_bpermute_b32 v107, v250, v91
	ds_bpermute_b32 v108, v250, v92
	ds_bpermute_b32 v109, v250, v93
	s_waitcnt lgkmcnt(0)
	v_pk_mul_f32 v[104:105], v[60:61], v[104:105]
	v_pk_mul_f32 v[102:103], v[58:59], v[102:103]
	v_pk_mul_f32 v[108:109], v[72:73], v[108:109]
	v_pk_mul_f32 v[106:107], v[70:71], v[106:107]
	v_pk_fma_f32 v[102:103], v[94:95], v[54:55], v[102:103]
	v_pk_fma_f32 v[104:105], v[96:97], v[56:57], v[104:105]
	v_pk_fma_f32 v[106:107], v[90:91], v[42:43], v[106:107]
	v_pk_fma_f32 v[108:109], v[92:93], v[44:45], v[108:109]
	v_cndmask_b32_e64 v97, v97, v105, s[4:5]
	v_cndmask_b32_e64 v96, v96, v104, s[4:5]
	v_cndmask_b32_e64 v95, v95, v103, s[4:5]
	v_cndmask_b32_e64 v94, v94, v102, s[4:5]
	v_cndmask_b32_e64 v93, v93, v109, s[4:5]
	v_cndmask_b32_e64 v92, v92, v108, s[4:5]
	v_cndmask_b32_e64 v91, v91, v107, s[4:5]
	v_cndmask_b32_e64 v90, v90, v106, s[4:5]
.LBB0_208:
	v_cvt_pk_bf16_f32 v94, v94, v95
	v_cvt_pk_bf16_f32 v95, v96, v97
	v_cvt_pk_bf16_f32 v96, v90, v91
	v_mov_b64_e32 v[90:91], s[56:57]
	v_mad_i64_i32 v[90:91], s[12:13], v98, s87, v[90:91]
	v_lshl_add_u64 v[90:91], s[34:35], 1, v[90:91]
	v_mov_b32_e32 v101, v100
	v_cvt_pk_bf16_f32 v97, v92, v93
	v_lshl_add_u64 v[90:91], v[90:91], 0, s[90:91]
	v_mov_b32_e32 v92, v100
	v_mov_b32_e32 v93, v100
	v_lshl_add_u64 v[90:91], v[90:91], 0, v[0:1]
	v_pk_mul_f32 v[88:89], v[88:89], v[92:93]
	v_pk_mul_f32 v[86:87], v[86:87], v[100:101]
	v_pk_mul_f32 v[84:85], v[84:85], v[92:93]
	s_and_b64 vcc, exec, s[10:11]
	v_pk_mul_f32 v[82:83], v[82:83], v[100:101]
	global_store_dwordx4 v[90:91], v[94:97], off
	s_cbranch_vccnz .LBB0_210
	ds_bpermute_b32 v92, v250, v86
	ds_bpermute_b32 v93, v250, v87
	ds_bpermute_b32 v94, v250, v88
	ds_bpermute_b32 v95, v250, v89
	ds_bpermute_b32 v96, v250, v82
	ds_bpermute_b32 v97, v250, v83
	ds_bpermute_b32 v98, v250, v84
	ds_bpermute_b32 v99, v250, v85
	s_waitcnt lgkmcnt(0)
	v_pk_mul_f32 v[94:95], v[60:61], v[94:95]
	v_pk_mul_f32 v[92:93], v[58:59], v[92:93]
	v_pk_mul_f32 v[98:99], v[72:73], v[98:99]
	v_pk_mul_f32 v[96:97], v[70:71], v[96:97]
	v_pk_fma_f32 v[92:93], v[86:87], v[54:55], v[92:93]
	v_pk_fma_f32 v[94:95], v[88:89], v[56:57], v[94:95]
	v_pk_fma_f32 v[96:97], v[82:83], v[42:43], v[96:97]
	v_pk_fma_f32 v[98:99], v[84:85], v[44:45], v[98:99]
	v_cndmask_b32_e64 v89, v89, v95, s[4:5]
	v_cndmask_b32_e64 v88, v88, v94, s[4:5]
	v_cndmask_b32_e64 v87, v87, v93, s[4:5]
	v_cndmask_b32_e64 v86, v86, v92, s[4:5]
	v_cndmask_b32_e64 v85, v85, v99, s[4:5]
	v_cndmask_b32_e64 v84, v84, v98, s[4:5]
	v_cndmask_b32_e64 v83, v83, v97, s[4:5]
	v_cndmask_b32_e64 v82, v82, v96, s[4:5]

.LBB0_212:
	s_waitcnt vmcnt(0)
	v_ffbh_u32_e32 v83, v85
	v_min_u32_e32 v83, 32, v83
	v_lshlrev_b64 v[84:85], v83, v[84:85]
	v_min_u32_e32 v84, 1, v84
	v_or_b32_e32 v84, v85, v84
	v_cvt_f32_u32_e32 v84, v84
	v_sub_u32_e32 v83, 32, v83
	s_and_b64 vcc, exec, s[10:11]
	v_ldexp_f32 v83, v84, v83
	v_mul_f32_e32 v83, 0x37800000, v83
	v_fmamk_f32 v83, v83, 0x3a800000, v195
	v_rsq_f32_e32 v83, v83
	s_nop 0
	v_mul_f32_e32 v84, v185, v83
	v_pk_mul_f32 v[80:81], v[80:81], v[84:85] op_sel_hi:[1,0]
	v_pk_mul_f32 v[78:79], v[78:79], v[84:85] op_sel_hi:[1,0]
	v_pk_mul_f32 v[76:77], v[76:77], v[84:85] op_sel_hi:[1,0]
	v_pk_mul_f32 v[74:75], v[74:75], v[84:85] op_sel_hi:[1,0]
	s_cbranch_vccnz .LBB0_214
	ds_bpermute_b32 v86, v250, v78
	ds_bpermute_b32 v87, v250, v79
	ds_bpermute_b32 v88, v250, v80
	ds_bpermute_b32 v89, v250, v81
	ds_bpermute_b32 v90, v250, v74
	ds_bpermute_b32 v91, v250, v75
	ds_bpermute_b32 v92, v250, v76
	ds_bpermute_b32 v93, v250, v77
	s_waitcnt lgkmcnt(0)
	v_pk_mul_f32 v[88:89], v[60:61], v[88:89]
	v_pk_mul_f32 v[86:87], v[58:59], v[86:87]
	v_pk_mul_f32 v[92:93], v[72:73], v[92:93]
	v_pk_mul_f32 v[90:91], v[70:71], v[90:91]
	v_pk_fma_f32 v[86:87], v[78:79], v[54:55], v[86:87]
	v_pk_fma_f32 v[88:89], v[80:81], v[56:57], v[88:89]
	v_pk_fma_f32 v[90:91], v[74:75], v[42:43], v[90:91]
	v_pk_fma_f32 v[92:93], v[76:77], v[44:45], v[92:93]
	v_cndmask_b32_e64 v81, v81, v89, s[4:5]
	v_cndmask_b32_e64 v80, v80, v88, s[4:5]
	v_cndmask_b32_e64 v79, v79, v87, s[4:5]
	v_cndmask_b32_e64 v78, v78, v86, s[4:5]
	v_cndmask_b32_e64 v77, v77, v93, s[4:5]
	v_cndmask_b32_e64 v76, v76, v92, s[4:5]
	v_cndmask_b32_e64 v75, v75, v91, s[4:5]
	v_cndmask_b32_e64 v74, v74, v90, s[4:5]
.LBB0_214:
	v_cvt_pk_bf16_f32 v78, v78, v79
	v_cvt_pk_bf16_f32 v79, v80, v81
	v_cvt_pk_bf16_f32 v80, v74, v75
	v_mov_b64_e32 v[74:75], s[56:57]
	v_mad_i64_i32 v[74:75], s[12:13], v82, s87, v[74:75]
	v_lshl_add_u64 v[74:75], s[34:35], 1, v[74:75]
	v_mov_b32_e32 v85, v84
	v_cvt_pk_bf16_f32 v81, v76, v77
	v_lshl_add_u64 v[74:75], v[74:75], 0, s[90:91]
	v_mov_b32_e32 v76, v84
	v_mov_b32_e32 v77, v84
	v_lshl_add_u64 v[74:75], v[74:75], 0, v[0:1]
	v_pk_mul_f32 v[68:69], v[68:69], v[76:77]
	v_pk_mul_f32 v[66:67], v[66:67], v[84:85]
	v_pk_mul_f32 v[64:65], v[64:65], v[76:77]
	s_and_b64 vcc, exec, s[10:11]
	v_pk_mul_f32 v[62:63], v[62:63], v[84:85]
	global_store_dwordx4 v[74:75], v[78:81], off
	s_cbranch_vccnz .LBB0_216
	ds_bpermute_b32 v76, v250, v66
	ds_bpermute_b32 v77, v250, v67
	ds_bpermute_b32 v78, v250, v68
	ds_bpermute_b32 v79, v250, v69
	ds_bpermute_b32 v80, v250, v62
	ds_bpermute_b32 v81, v250, v63
	ds_bpermute_b32 v82, v250, v64
	ds_bpermute_b32 v83, v250, v65
	s_waitcnt lgkmcnt(0)
	v_pk_mul_f32 v[78:79], v[60:61], v[78:79]
	v_pk_mul_f32 v[76:77], v[58:59], v[76:77]
	v_pk_mul_f32 v[82:83], v[72:73], v[82:83]
	v_pk_mul_f32 v[80:81], v[70:71], v[80:81]
	v_pk_fma_f32 v[76:77], v[66:67], v[54:55], v[76:77]
	v_pk_fma_f32 v[78:79], v[68:69], v[56:57], v[78:79]
	v_pk_fma_f32 v[80:81], v[62:63], v[42:43], v[80:81]
	v_pk_fma_f32 v[82:83], v[64:65], v[44:45], v[82:83]
	v_cndmask_b32_e64 v69, v69, v79, s[4:5]
	v_cndmask_b32_e64 v68, v68, v78, s[4:5]
	v_cndmask_b32_e64 v67, v67, v77, s[4:5]
	v_cndmask_b32_e64 v66, v66, v76, s[4:5]
	v_cndmask_b32_e64 v65, v65, v83, s[4:5]
	v_cndmask_b32_e64 v64, v64, v82, s[4:5]
	v_cndmask_b32_e64 v63, v63, v81, s[4:5]
	v_cndmask_b32_e64 v62, v62, v80, s[4:5]

.LBB0_218:
	s_waitcnt vmcnt(0)
	v_ffbh_u32_e32 v63, v65
	v_min_u32_e32 v63, 32, v63
	v_lshlrev_b64 v[64:65], v63, v[64:65]
	v_min_u32_e32 v64, 1, v64
	v_or_b32_e32 v64, v65, v64
	v_cvt_f32_u32_e32 v64, v64
	v_sub_u32_e32 v63, 32, v63
	s_and_b64 vcc, exec, s[10:11]
	v_ldexp_f32 v63, v64, v63
	v_mul_f32_e32 v63, 0x37800000, v63
	v_fmamk_f32 v63, v63, 0x3a800000, v195
	v_rsq_f32_e32 v63, v63
	s_nop 0
	v_mul_f32_e32 v64, v185, v63
	v_pk_mul_f32 v[52:53], v[52:53], v[64:65] op_sel_hi:[1,0]
	v_pk_mul_f32 v[50:51], v[50:51], v[64:65] op_sel_hi:[1,0]
	v_pk_mul_f32 v[48:49], v[48:49], v[64:65] op_sel_hi:[1,0]
	v_pk_mul_f32 v[46:47], v[46:47], v[64:65] op_sel_hi:[1,0]
	s_cbranch_vccnz .LBB0_220
	ds_bpermute_b32 v66, v250, v50
	ds_bpermute_b32 v67, v250, v51
	ds_bpermute_b32 v68, v250, v52
	ds_bpermute_b32 v69, v250, v53
	ds_bpermute_b32 v74, v250, v46
	ds_bpermute_b32 v75, v250, v47
	ds_bpermute_b32 v76, v250, v48
	ds_bpermute_b32 v77, v250, v49
	s_waitcnt lgkmcnt(0)
	v_pk_mul_f32 v[68:69], v[60:61], v[68:69]
	v_pk_mul_f32 v[66:67], v[58:59], v[66:67]
	v_pk_mul_f32 v[76:77], v[72:73], v[76:77]
	v_pk_mul_f32 v[74:75], v[70:71], v[74:75]
	v_pk_fma_f32 v[66:67], v[50:51], v[54:55], v[66:67]
	v_pk_fma_f32 v[68:69], v[52:53], v[56:57], v[68:69]
	v_pk_fma_f32 v[74:75], v[46:47], v[42:43], v[74:75]
	v_pk_fma_f32 v[76:77], v[48:49], v[44:45], v[76:77]
	v_cndmask_b32_e64 v53, v53, v69, s[4:5]
	v_cndmask_b32_e64 v52, v52, v68, s[4:5]
	v_cndmask_b32_e64 v51, v51, v67, s[4:5]
	v_cndmask_b32_e64 v50, v50, v66, s[4:5]
	v_cndmask_b32_e64 v49, v49, v77, s[4:5]
	v_cndmask_b32_e64 v48, v48, v76, s[4:5]
	v_cndmask_b32_e64 v47, v47, v75, s[4:5]
	v_cndmask_b32_e64 v46, v46, v74, s[4:5]
.LBB0_220:
	v_cvt_pk_bf16_f32 v50, v50, v51
	v_cvt_pk_bf16_f32 v51, v52, v53
	v_cvt_pk_bf16_f32 v52, v46, v47
	v_mov_b64_e32 v[46:47], s[56:57]
	v_mad_i64_i32 v[46:47], s[12:13], v62, s87, v[46:47]
	v_lshl_add_u64 v[46:47], s[34:35], 1, v[46:47]
	v_mov_b32_e32 v65, v64
	v_cvt_pk_bf16_f32 v53, v48, v49
	v_lshl_add_u64 v[46:47], v[46:47], 0, s[90:91]
	v_mov_b32_e32 v48, v64
	v_mov_b32_e32 v49, v64
	v_lshl_add_u64 v[46:47], v[46:47], 0, v[0:1]
	v_pk_mul_f32 v[40:41], v[40:41], v[48:49]
	v_pk_mul_f32 v[38:39], v[38:39], v[64:65]
	v_pk_mul_f32 v[36:37], v[36:37], v[48:49]
	s_and_b64 vcc, exec, s[10:11]
	v_pk_mul_f32 v[34:35], v[34:35], v[64:65]
	global_store_dwordx4 v[46:47], v[50:53], off
	s_cbranch_vccnz .LBB0_222
	ds_bpermute_b32 v48, v250, v38
	ds_bpermute_b32 v49, v250, v39
	ds_bpermute_b32 v50, v250, v40
	ds_bpermute_b32 v51, v250, v41
	ds_bpermute_b32 v52, v250, v34
	ds_bpermute_b32 v53, v250, v35
	ds_bpermute_b32 v62, v250, v36
	ds_bpermute_b32 v63, v250, v37
	s_waitcnt lgkmcnt(0)
	v_pk_mul_f32 v[50:51], v[60:61], v[50:51]
	v_pk_mul_f32 v[48:49], v[58:59], v[48:49]
	v_pk_mul_f32 v[62:63], v[72:73], v[62:63]
	v_pk_mul_f32 v[52:53], v[70:71], v[52:53]
	v_pk_fma_f32 v[48:49], v[38:39], v[54:55], v[48:49]
	v_pk_fma_f32 v[50:51], v[40:41], v[56:57], v[50:51]
	v_pk_fma_f32 v[52:53], v[34:35], v[42:43], v[52:53]
	v_pk_fma_f32 v[62:63], v[36:37], v[44:45], v[62:63]
	v_cndmask_b32_e64 v41, v41, v51, s[4:5]
	v_cndmask_b32_e64 v40, v40, v50, s[4:5]
	v_cndmask_b32_e64 v39, v39, v49, s[4:5]
	v_cndmask_b32_e64 v38, v38, v48, s[4:5]
	v_cndmask_b32_e64 v37, v37, v63, s[4:5]
	v_cndmask_b32_e64 v36, v36, v62, s[4:5]
	v_cndmask_b32_e64 v35, v35, v53, s[4:5]
	v_cndmask_b32_e64 v34, v34, v52, s[4:5]

.LBB0_224:
	s_waitcnt vmcnt(0)
	v_ffbh_u32_e32 v35, v37
	v_min_u32_e32 v35, 32, v35
	v_lshlrev_b64 v[36:37], v35, v[36:37]
	v_min_u32_e32 v36, 1, v36
	v_or_b32_e32 v36, v37, v36
	v_cvt_f32_u32_e32 v36, v36
	v_sub_u32_e32 v35, 32, v35
	s_and_b64 vcc, exec, s[10:11]
	v_ldexp_f32 v35, v36, v35
	v_mul_f32_e32 v35, 0x37800000, v35
	v_fmamk_f32 v35, v35, 0x3a800000, v195
	v_rsq_f32_e32 v35, v35
	s_nop 0
	v_mul_f32_e32 v36, v185, v35
	v_pk_mul_f32 v[32:33], v[32:33], v[36:37] op_sel_hi:[1,0]
	v_pk_mul_f32 v[30:31], v[30:31], v[36:37] op_sel_hi:[1,0]
	v_pk_mul_f32 v[28:29], v[28:29], v[36:37] op_sel_hi:[1,0]
	v_pk_mul_f32 v[26:27], v[26:27], v[36:37] op_sel_hi:[1,0]
	s_cbranch_vccnz .LBB0_226
	ds_bpermute_b32 v38, v250, v30
	ds_bpermute_b32 v39, v250, v31
	ds_bpermute_b32 v40, v250, v32
	ds_bpermute_b32 v41, v250, v33
	ds_bpermute_b32 v46, v250, v26
	ds_bpermute_b32 v47, v250, v27
	ds_bpermute_b32 v48, v250, v28
	ds_bpermute_b32 v49, v250, v29
	s_waitcnt lgkmcnt(0)
	v_pk_mul_f32 v[40:41], v[60:61], v[40:41]
	v_pk_mul_f32 v[38:39], v[58:59], v[38:39]
	v_pk_mul_f32 v[48:49], v[72:73], v[48:49]
	v_pk_mul_f32 v[46:47], v[70:71], v[46:47]
	v_pk_fma_f32 v[38:39], v[30:31], v[54:55], v[38:39]
	v_pk_fma_f32 v[40:41], v[32:33], v[56:57], v[40:41]
	v_pk_fma_f32 v[46:47], v[26:27], v[42:43], v[46:47]
	v_pk_fma_f32 v[48:49], v[28:29], v[44:45], v[48:49]
	v_cndmask_b32_e64 v33, v33, v41, s[4:5]
	v_cndmask_b32_e64 v32, v32, v40, s[4:5]
	v_cndmask_b32_e64 v31, v31, v39, s[4:5]
	v_cndmask_b32_e64 v30, v30, v38, s[4:5]
	v_cndmask_b32_e64 v29, v29, v49, s[4:5]
	v_cndmask_b32_e64 v28, v28, v48, s[4:5]
	v_cndmask_b32_e64 v27, v27, v47, s[4:5]
	v_cndmask_b32_e64 v26, v26, v46, s[4:5]
.LBB0_226:
	v_cvt_pk_bf16_f32 v30, v30, v31
	v_cvt_pk_bf16_f32 v31, v32, v33
	v_cvt_pk_bf16_f32 v32, v26, v27
	v_mov_b64_e32 v[26:27], s[56:57]
	v_mad_i64_i32 v[26:27], s[12:13], v34, s87, v[26:27]
	v_lshl_add_u64 v[26:27], s[34:35], 1, v[26:27]
	v_mov_b32_e32 v37, v36
	v_cvt_pk_bf16_f32 v33, v28, v29
	v_lshl_add_u64 v[26:27], v[26:27], 0, s[90:91]
	v_mov_b32_e32 v28, v36
	v_mov_b32_e32 v29, v36
	v_lshl_add_u64 v[26:27], v[26:27], 0, v[0:1]
	v_pk_mul_f32 v[24:25], v[24:25], v[28:29]
	v_pk_mul_f32 v[22:23], v[22:23], v[36:37]
	v_pk_mul_f32 v[20:21], v[20:21], v[28:29]
	s_and_b64 vcc, exec, s[10:11]
	v_pk_mul_f32 v[18:19], v[18:19], v[36:37]
	global_store_dwordx4 v[26:27], v[30:33], off
	s_cbranch_vccnz .LBB0_228
	ds_bpermute_b32 v28, v250, v22
	ds_bpermute_b32 v29, v250, v23
	ds_bpermute_b32 v30, v250, v24
	ds_bpermute_b32 v31, v250, v25
	ds_bpermute_b32 v32, v250, v18
	ds_bpermute_b32 v33, v250, v19
	ds_bpermute_b32 v34, v250, v20
	ds_bpermute_b32 v35, v250, v21
	s_waitcnt lgkmcnt(0)
	v_pk_mul_f32 v[30:31], v[60:61], v[30:31]
	v_pk_mul_f32 v[28:29], v[58:59], v[28:29]
	v_pk_mul_f32 v[34:35], v[72:73], v[34:35]
	v_pk_mul_f32 v[32:33], v[70:71], v[32:33]
	v_pk_fma_f32 v[28:29], v[22:23], v[54:55], v[28:29]
	v_pk_fma_f32 v[30:31], v[24:25], v[56:57], v[30:31]
	v_pk_fma_f32 v[32:33], v[18:19], v[42:43], v[32:33]
	v_pk_fma_f32 v[34:35], v[20:21], v[44:45], v[34:35]
	v_cndmask_b32_e64 v25, v25, v31, s[4:5]
	v_cndmask_b32_e64 v24, v24, v30, s[4:5]
	v_cndmask_b32_e64 v23, v23, v29, s[4:5]
	v_cndmask_b32_e64 v22, v22, v28, s[4:5]
	v_cndmask_b32_e64 v21, v21, v35, s[4:5]
	v_cndmask_b32_e64 v20, v20, v34, s[4:5]
	v_cndmask_b32_e64 v19, v19, v33, s[4:5]
	v_cndmask_b32_e64 v18, v18, v32, s[4:5]

.LBB0_230:
	s_waitcnt vmcnt(0)
	v_ffbh_u32_e32 v19, v21
	v_min_u32_e32 v19, 32, v19
	v_lshlrev_b64 v[20:21], v19, v[20:21]
	v_min_u32_e32 v20, 1, v20
	v_or_b32_e32 v20, v21, v20
	v_cvt_f32_u32_e32 v20, v20
	v_sub_u32_e32 v19, 32, v19
	s_and_b64 vcc, exec, s[10:11]
	v_ldexp_f32 v19, v20, v19
	v_mul_f32_e32 v19, 0x37800000, v19
	v_fmamk_f32 v19, v19, 0x3a800000, v195
	v_rsq_f32_e32 v19, v19
	s_nop 0
	v_mul_f32_e32 v20, v185, v19
	v_pk_mul_f32 v[16:17], v[16:17], v[20:21] op_sel_hi:[1,0]
	v_pk_mul_f32 v[14:15], v[14:15], v[20:21] op_sel_hi:[1,0]
	v_pk_mul_f32 v[12:13], v[12:13], v[20:21] op_sel_hi:[1,0]
	v_pk_mul_f32 v[10:11], v[10:11], v[20:21] op_sel_hi:[1,0]
	s_cbranch_vccnz .LBB0_232
	ds_bpermute_b32 v22, v250, v14
	ds_bpermute_b32 v23, v250, v15
	ds_bpermute_b32 v24, v250, v16
	ds_bpermute_b32 v25, v250, v17
	ds_bpermute_b32 v26, v250, v10
	ds_bpermute_b32 v27, v250, v11
	ds_bpermute_b32 v28, v250, v12
	ds_bpermute_b32 v29, v250, v13
	s_waitcnt lgkmcnt(0)
	v_pk_mul_f32 v[24:25], v[60:61], v[24:25]
	v_pk_mul_f32 v[22:23], v[58:59], v[22:23]
	v_pk_mul_f32 v[28:29], v[72:73], v[28:29]
	v_pk_mul_f32 v[26:27], v[70:71], v[26:27]
	v_pk_fma_f32 v[22:23], v[14:15], v[54:55], v[22:23]
	v_pk_fma_f32 v[24:25], v[16:17], v[56:57], v[24:25]
	v_pk_fma_f32 v[26:27], v[10:11], v[42:43], v[26:27]
	v_pk_fma_f32 v[28:29], v[12:13], v[44:45], v[28:29]
	v_cndmask_b32_e64 v17, v17, v25, s[4:5]
	v_cndmask_b32_e64 v16, v16, v24, s[4:5]
	v_cndmask_b32_e64 v15, v15, v23, s[4:5]
	v_cndmask_b32_e64 v14, v14, v22, s[4:5]
	v_cndmask_b32_e64 v13, v13, v29, s[4:5]
	v_cndmask_b32_e64 v12, v12, v28, s[4:5]
	v_cndmask_b32_e64 v11, v11, v27, s[4:5]
	v_cndmask_b32_e64 v10, v10, v26, s[4:5]
.LBB0_232:
	v_cvt_pk_bf16_f32 v14, v14, v15
	v_cvt_pk_bf16_f32 v15, v16, v17
	v_cvt_pk_bf16_f32 v16, v10, v11
	v_mov_b64_e32 v[10:11], s[56:57]
	v_mad_i64_i32 v[10:11], s[12:13], v18, s87, v[10:11]
	v_lshl_add_u64 v[10:11], s[34:35], 1, v[10:11]
	v_mov_b32_e32 v21, v20
	v_cvt_pk_bf16_f32 v17, v12, v13
	v_lshl_add_u64 v[10:11], v[10:11], 0, s[90:91]
	v_mov_b32_e32 v12, v20
	v_mov_b32_e32 v13, v20
	v_lshl_add_u64 v[10:11], v[10:11], 0, v[0:1]
	v_pk_mul_f32 v[8:9], v[8:9], v[12:13]
	v_pk_mul_f32 v[6:7], v[6:7], v[20:21]
	v_pk_mul_f32 v[4:5], v[4:5], v[12:13]
	s_and_b64 vcc, exec, s[10:11]
	v_pk_mul_f32 v[2:3], v[2:3], v[20:21]
	global_store_dwordx4 v[10:11], v[14:17], off
	s_cbranch_vccnz .LBB0_234
	ds_bpermute_b32 v12, v250, v6
	ds_bpermute_b32 v13, v250, v7
	ds_bpermute_b32 v14, v250, v8
	ds_bpermute_b32 v15, v250, v9
	ds_bpermute_b32 v16, v250, v2
	ds_bpermute_b32 v17, v250, v3
	ds_bpermute_b32 v18, v250, v4
	ds_bpermute_b32 v19, v250, v5
	s_waitcnt lgkmcnt(0)
	v_pk_mul_f32 v[14:15], v[60:61], v[14:15]
	v_pk_mul_f32 v[12:13], v[58:59], v[12:13]
	v_pk_mul_f32 v[18:19], v[72:73], v[18:19]
	v_pk_mul_f32 v[16:17], v[70:71], v[16:17]
	v_pk_fma_f32 v[12:13], v[6:7], v[54:55], v[12:13]
	v_pk_fma_f32 v[14:15], v[8:9], v[56:57], v[14:15]
	v_pk_fma_f32 v[16:17], v[2:3], v[42:43], v[16:17]
	v_pk_fma_f32 v[18:19], v[4:5], v[44:45], v[18:19]
	v_cndmask_b32_e64 v9, v9, v15, s[4:5]
	v_cndmask_b32_e64 v8, v8, v14, s[4:5]
	v_cndmask_b32_e64 v7, v7, v13, s[4:5]
	v_cndmask_b32_e64 v6, v6, v12, s[4:5]
	v_cndmask_b32_e64 v5, v5, v19, s[4:5]
	v_cndmask_b32_e64 v4, v4, v18, s[4:5]
	v_cndmask_b32_e64 v3, v3, v17, s[4:5]
	v_cndmask_b32_e64 v2, v2, v16, s[4:5]
